# GEMM K-loop heads aligned to 64 bytes
# speedup vs baseline: 1.0007x; 1.0007x over previous
;   __device__ __forceinline__ const char* aptr(const Unit& u) const { return s.aptr(u); }
;   __device__ __forceinline__ const char* bptr(const Unit& u) const { return s.bptr(u); }
;   __device__ __forceinline__ bool next(int i, Unit& u) const { if (i) return false; u = u0; return true; }
; template <class Epi, class Sched>
; __device__ __forceinline__ void gemm_phase(PG8_LAS unsigned char* lds, const int lda, const int ldb, const Sched& S, const Epi& E) {
;     ...
;     const bool has_next = S.next(ui + 1, nxt);
;     const char* nA = has_next ? S.aptr(nxt) : cA; const char* nB = has_next ? S.bptr(nxt) : cB;
; #pragma unroll 1
;     for (int t = 0; t < nt; t += 2) {
;       const bool last = (t == nt - 2);
;       const char* a1 = cA + (size_t)(t + 1) * kstep;
;       const char* a2 = last ? nA : cA + (size_t)(t + 2) * kstep; const char* b2 = last ? nB : cB + (size_t)(t + 2) * kstep;
;     ...
;     for (int a = 0; a < 2; ++a)
; #pragma unroll
;       for (int b = 0; b < 2; ++b)
; #pragma unroll
;         for (int m = 0; m < 4; ++m)
; #pragma unroll
;           for (int n = 0; n < 2; ++n) acc[a][b][m][n] = (f32x4){0.f, 0.f, 0.f, 0.f};
.LBB0_334:
	s_ashr_i32 s17, s16, 31
	s_xor_b64 s[20:21], s[24:25], -1
	s_lshl_b64 s[18:19], s[16:17], 19
	s_add_u32 s18, s58, s18
	s_addc_u32 s19, s59, s19
	s_and_b64 s[22:23], s[24:25], exec
	s_cselect_b32 s17, s19, s9
	s_cselect_b32 s26, s18, s8
	s_ashr_i32 s15, s14, 31
	s_lshl_b64 s[22:23], s[14:15], 19
	v_readlane_b32 s15, v255, 29
	s_add_u32 s22, s15, s22
	v_readlane_b32 s15, v255, 30
	s_addc_u32 s23, s15, s23
	s_and_b64 s[24:25], s[24:25], exec
	s_cselect_b32 s15, s23, s11
	s_cselect_b32 s27, s22, s10
	s_add_u32 s8, s8, 0x40080
	s_addc_u32 s9, s9, 0
	s_add_u32 s28, s10, 0x100
	v_mov_b32_e32 v2, 0
	s_addc_u32 s29, s11, 0
	s_mov_b32 s30, -2
	v_mov_b32_e32 v3, v2
	v_mov_b64_e32 v[4:5], 0
	v_mov_b64_e32 v[6:7], 0
	v_mov_b64_e32 v[8:9], 0
	v_mov_b64_e32 v[10:11], 0
	v_mov_b64_e32 v[12:13], 0
	v_mov_b64_e32 v[14:15], 0
	v_mov_b64_e32 v[16:17], 0
	v_mov_b64_e32 v[18:19], 0
	v_mov_b64_e32 v[20:21], 0
	v_mov_b64_e32 v[22:23], 0
	v_mov_b64_e32 v[24:25], 0
	v_mov_b64_e32 v[26:27], 0
	v_mov_b64_e32 v[28:29], 0
	v_mov_b64_e32 v[30:31], 0
	v_mov_b64_e32 v[32:33], 0
	v_mov_b64_e32 v[34:35], 0
	v_mov_b64_e32 v[36:37], 0
	v_mov_b64_e32 v[38:39], 0
	v_mov_b64_e32 v[40:41], 0
	v_mov_b64_e32 v[42:43], 0
	v_mov_b64_e32 v[44:45], 0
	v_mov_b64_e32 v[46:47], 0
	v_mov_b64_e32 v[48:49], 0
	v_mov_b64_e32 v[50:51], 0
	v_mov_b64_e32 v[52:53], 0
	v_mov_b64_e32 v[54:55], 0
	v_mov_b64_e32 v[56:57], 0
	v_mov_b64_e32 v[58:59], 0
	v_mov_b64_e32 v[60:61], 0
	v_mov_b64_e32 v[62:63], 0
	v_mov_b64_e32 v[64:65], 0
	v_mov_b64_e32 v[66:67], 0
	v_mov_b64_e32 v[68:69], 0
	v_mov_b64_e32 v[70:71], 0
	v_mov_b64_e32 v[72:73], 0
	v_mov_b64_e32 v[74:75], 0
	v_mov_b64_e32 v[76:77], 0
	v_mov_b64_e32 v[78:79], 0
	v_mov_b64_e32 v[80:81], 0
	v_mov_b64_e32 v[82:83], 0
	v_mov_b64_e32 v[84:85], 0
	v_mov_b64_e32 v[86:87], 0
	v_mov_b64_e32 v[88:89], 0
	v_mov_b64_e32 v[90:91], 0
	v_mov_b64_e32 v[92:93], 0
	v_mov_b64_e32 v[94:95], 0
	v_mov_b64_e32 v[96:97], 0
	v_mov_b64_e32 v[98:99], 0
	v_mov_b64_e32 v[100:101], 0
	v_mov_b64_e32 v[102:103], 0
	v_mov_b64_e32 v[104:105], 0
	v_mov_b64_e32 v[106:107], 0
	v_mov_b64_e32 v[108:109], 0
	v_mov_b64_e32 v[110:111], 0
	v_mov_b64_e32 v[112:113], 0
	v_mov_b64_e32 v[114:115], 0
	v_mov_b64_e32 v[116:117], 0
	v_mov_b64_e32 v[118:119], 0
	v_mov_b64_e32 v[120:121], 0
	v_mov_b64_e32 v[122:123], 0
	v_mov_b64_e32 v[124:125], 0
	v_mov_b64_e32 v[126:127], 0
	v_mov_b64_e32 v[128:129], 0
	.p2align	6

;   __device__ __forceinline__ const char* aptr(const Unit& u) const { return s.aptr(u); }
;   __device__ __forceinline__ const char* bptr(const Unit& u) const { return s.bptr(u); }
;   __device__ __forceinline__ bool next(int i, Unit& u) const { if (i) return false; u = u0; return true; }
; template <class Epi, class Sched>
; __device__ __forceinline__ void gemm_phase(PG8_LAS unsigned char* lds, const int lda, const int ldb, const Sched& S, const Epi& E) {
;     ...
;     const bool has_next = S.next(ui + 1, nxt);
;     const char* nA = has_next ? S.aptr(nxt) : cA; const char* nB = has_next ? S.bptr(nxt) : cB;
; #pragma unroll 1
;     for (int t = 0; t < nt; t += 2) {
;       const bool last = (t == nt - 2);
;       const char* a1 = cA + (size_t)(t + 1) * kstep;
;       const char* a2 = last ? nA : cA + (size_t)(t + 2) * kstep; const char* b2 = last ? nB : cB + (size_t)(t + 2) * kstep;
;     ...
;     for (int a = 0; a < 2; ++a)
; #pragma unroll
;       for (int b = 0; b < 2; ++b)
; #pragma unroll
;         for (int m = 0; m < 4; ++m)
; #pragma unroll
;           for (int n = 0; n < 2; ++n) acc[a][b][m][n] = (f32x4){0.f, 0.f, 0.f, 0.f};
.LBB0_684:
	v_mov_b64_e32 v[2:3], 0xa20
	s_ashr_i32 s19, s18, 31
	v_cmp_lt_i64_e32 vcc, s[20:21], v[2:3]
	s_lshl_b64 s[20:21], s[18:19], 19
	s_add_u32 s20, s58, s20
	s_addc_u32 s21, s59, s21
	s_and_b64 s[22:23], vcc, exec
	s_cselect_b32 s19, s21, s11
	s_cselect_b32 s26, s20, s10
	s_ashr_i32 s17, s16, 31
	s_lshl_b64 s[22:23], s[16:17], 19
	v_readlane_b32 s17, v255, 29
	s_add_u32 s22, s17, s22
	v_readlane_b32 s17, v255, 30
	s_addc_u32 s23, s17, s23
	s_and_b64 s[24:25], vcc, exec
	s_cselect_b32 s17, s23, s13
	s_cselect_b32 s27, s22, s12
	s_add_u32 s10, s10, 0x40080
	s_addc_u32 s11, s11, 0
	s_add_u32 s28, s12, 0x100
	v_mov_b32_e32 v2, 0
	s_addc_u32 s29, s13, 0
	s_mov_b32 s30, -2
	v_mov_b32_e32 v3, v2
	v_mov_b64_e32 v[4:5], 0
	v_mov_b64_e32 v[6:7], 0
	v_mov_b64_e32 v[8:9], 0
	v_mov_b64_e32 v[10:11], 0
	v_mov_b64_e32 v[12:13], 0
	v_mov_b64_e32 v[14:15], 0
	v_mov_b64_e32 v[16:17], 0
	v_mov_b64_e32 v[18:19], 0
	v_mov_b64_e32 v[20:21], 0
	v_mov_b64_e32 v[22:23], 0
	v_mov_b64_e32 v[24:25], 0
	v_mov_b64_e32 v[26:27], 0
	v_mov_b64_e32 v[28:29], 0
	v_mov_b64_e32 v[30:31], 0
	v_mov_b64_e32 v[32:33], 0
	v_mov_b64_e32 v[34:35], 0
	v_mov_b64_e32 v[36:37], 0
	v_mov_b64_e32 v[38:39], 0
	v_mov_b64_e32 v[40:41], 0
	v_mov_b64_e32 v[42:43], 0
	v_mov_b64_e32 v[44:45], 0
	v_mov_b64_e32 v[46:47], 0
	v_mov_b64_e32 v[48:49], 0
	v_mov_b64_e32 v[50:51], 0
	v_mov_b64_e32 v[52:53], 0
	v_mov_b64_e32 v[54:55], 0
	v_mov_b64_e32 v[56:57], 0
	v_mov_b64_e32 v[58:59], 0
	v_mov_b64_e32 v[60:61], 0
	v_mov_b64_e32 v[62:63], 0
	v_mov_b64_e32 v[64:65], 0
	v_mov_b64_e32 v[66:67], 0
	v_mov_b64_e32 v[68:69], 0
	v_mov_b64_e32 v[70:71], 0
	v_mov_b64_e32 v[72:73], 0
	v_mov_b64_e32 v[74:75], 0
	v_mov_b64_e32 v[76:77], 0
	v_mov_b64_e32 v[78:79], 0
	v_mov_b64_e32 v[80:81], 0
	v_mov_b64_e32 v[82:83], 0
	v_mov_b64_e32 v[84:85], 0
	v_mov_b64_e32 v[86:87], 0
	v_mov_b64_e32 v[88:89], 0
	v_mov_b64_e32 v[90:91], 0
	v_mov_b64_e32 v[92:93], 0
	v_mov_b64_e32 v[94:95], 0
	v_mov_b64_e32 v[96:97], 0
	v_mov_b64_e32 v[98:99], 0
	v_mov_b64_e32 v[100:101], 0
	v_mov_b64_e32 v[102:103], 0
	v_mov_b64_e32 v[104:105], 0
	v_mov_b64_e32 v[106:107], 0
	v_mov_b64_e32 v[108:109], 0
	v_mov_b64_e32 v[110:111], 0
	v_mov_b64_e32 v[112:113], 0
	v_mov_b64_e32 v[114:115], 0
	v_mov_b64_e32 v[116:117], 0
	v_mov_b64_e32 v[118:119], 0
	v_mov_b64_e32 v[120:121], 0
	v_mov_b64_e32 v[122:123], 0
	v_mov_b64_e32 v[124:125], 0
	v_mov_b64_e32 v[126:127], 0
	v_mov_b64_e32 v[128:129], 0
	.p2align	6

;   __device__ __forceinline__ const char* aptr(const Unit& u) const { return s.aptr(u); }
;   __device__ __forceinline__ const char* bptr(const Unit& u) const { return s.bptr(u); }
;   __device__ __forceinline__ bool next(int i, Unit& u) const { if (i) return false; u = u0; return true; }
; template <class Epi, class Sched>
; __device__ __forceinline__ void gemm_phase(PG8_LAS unsigned char* lds, const int lda, const int ldb, const Sched& S, const Epi& E) {
;     ...
;     const bool has_next = S.next(ui + 1, nxt);
;     const char* nA = has_next ? S.aptr(nxt) : cA; const char* nB = has_next ? S.bptr(nxt) : cB;
; #pragma unroll 1
;     for (int t = 0; t < nt; t += 2) {
;       const bool last = (t == nt - 2);
;       const char* a1 = cA + (size_t)(t + 1) * kstep;
;       const char* a2 = last ? nA : cA + (size_t)(t + 2) * kstep; const char* b2 = last ? nB : cB + (size_t)(t + 2) * kstep;
;     ...
;     for (int a = 0; a < 2; ++a)
; #pragma unroll
;       for (int b = 0; b < 2; ++b)
; #pragma unroll
;         for (int m = 0; m < 4; ++m)
; #pragma unroll
;           for (int n = 0; n < 2; ++n) acc[a][b][m][n] = (f32x4){0.f, 0.f, 0.f, 0.f};
.LBB0_1087:
	v_mov_b64_e32 v[2:3], 0x100
	s_ashr_i32 s7, s6, 31
	v_cmp_lt_i64_e32 vcc, s[8:9], v[2:3]
	s_lshl_b64 s[8:9], s[6:7], 21
	v_readlane_b32 s1, v254, 41
	s_add_u32 s8, s1, s8
	v_readlane_b32 s1, v254, 42
	s_addc_u32 s9, s1, s9
	s_and_b64 s[10:11], vcc, exec
	s_cselect_b32 s7, s9, s15
	s_cselect_b32 s13, s8, s14
	s_ashr_i32 s1, s0, 31
	s_lshl_b64 s[10:11], s[0:1], 21
	s_add_u32 s10, s69, s10
	v_readlane_b32 s1, v254, 40
	s_addc_u32 s11, s1, s11
	s_and_b64 s[18:19], vcc, exec
	s_cselect_b32 s1, s11, s17
	s_cselect_b32 s29, s10, s16
	s_add_u32 s14, s14, 0x100080
	s_addc_u32 s15, s15, 0
	s_add_u32 s30, s16, 0x100
	v_mov_b32_e32 v2, 0
	s_addc_u32 s31, s17, 0
	s_mov_b32 s34, -2
	v_mov_b32_e32 v3, v2
	v_mov_b64_e32 v[4:5], 0
	v_mov_b64_e32 v[6:7], 0
	v_mov_b64_e32 v[8:9], 0
	v_mov_b64_e32 v[10:11], 0
	v_mov_b64_e32 v[12:13], 0
	v_mov_b64_e32 v[14:15], 0
	v_mov_b64_e32 v[16:17], 0
	v_mov_b64_e32 v[18:19], 0
	v_mov_b64_e32 v[20:21], 0
	v_mov_b64_e32 v[22:23], 0
	v_mov_b64_e32 v[24:25], 0
	v_mov_b64_e32 v[26:27], 0
	v_mov_b64_e32 v[28:29], 0
	v_mov_b64_e32 v[30:31], 0
	v_mov_b64_e32 v[32:33], 0
	v_mov_b64_e32 v[34:35], 0
	v_mov_b64_e32 v[36:37], 0
	v_mov_b64_e32 v[38:39], 0
	v_mov_b64_e32 v[40:41], 0
	v_mov_b64_e32 v[42:43], 0
	v_mov_b64_e32 v[44:45], 0
	v_mov_b64_e32 v[46:47], 0
	v_mov_b64_e32 v[48:49], 0
	v_mov_b64_e32 v[50:51], 0
	v_mov_b64_e32 v[52:53], 0
	v_mov_b64_e32 v[54:55], 0
	v_mov_b64_e32 v[56:57], 0
	v_mov_b64_e32 v[58:59], 0
	v_mov_b64_e32 v[60:61], 0
	v_mov_b64_e32 v[62:63], 0
	v_mov_b64_e32 v[64:65], 0
	v_mov_b64_e32 v[66:67], 0
	v_mov_b64_e32 v[68:69], 0
	v_mov_b64_e32 v[70:71], 0
	v_mov_b64_e32 v[72:73], 0
	v_mov_b64_e32 v[74:75], 0
	v_mov_b64_e32 v[76:77], 0
	v_mov_b64_e32 v[78:79], 0
	v_mov_b64_e32 v[80:81], 0
	v_mov_b64_e32 v[82:83], 0
	v_mov_b64_e32 v[84:85], 0
	v_mov_b64_e32 v[86:87], 0
	v_mov_b64_e32 v[88:89], 0
	v_mov_b64_e32 v[90:91], 0
	v_mov_b64_e32 v[92:93], 0
	v_mov_b64_e32 v[94:95], 0
	v_mov_b64_e32 v[96:97], 0
	v_mov_b64_e32 v[98:99], 0
	v_mov_b64_e32 v[100:101], 0
	v_mov_b64_e32 v[102:103], 0
	v_mov_b64_e32 v[104:105], 0
	v_mov_b64_e32 v[106:107], 0
	v_mov_b64_e32 v[108:109], 0
	v_mov_b64_e32 v[110:111], 0
	v_mov_b64_e32 v[112:113], 0
	v_mov_b64_e32 v[114:115], 0
	v_mov_b64_e32 v[116:117], 0
	v_mov_b64_e32 v[118:119], 0
	v_mov_b64_e32 v[120:121], 0
	v_mov_b64_e32 v[122:123], 0
	v_mov_b64_e32 v[124:125], 0
	v_mov_b64_e32 v[126:127], 0
	v_mov_b64_e32 v[128:129], 0
	.p2align	6

;   __device__ __forceinline__ const char* aptr(const Unit& u) const { return s.aptr(u); }
;   __device__ __forceinline__ const char* bptr(const Unit& u) const { return s.bptr(u); }
;   __device__ __forceinline__ bool next(int i, Unit& u) const { if (i) return false; u = u0; return true; }
; template <class Epi, class Sched>
; __device__ __forceinline__ void gemm_phase(PG8_LAS unsigned char* lds, const int lda, const int ldb, const Sched& S, const Epi& E) {
;     ...
;     const bool has_next = S.next(ui + 1, nxt);
;     const char* nA = has_next ? S.aptr(nxt) : cA; const char* nB = has_next ? S.bptr(nxt) : cB;
; #pragma unroll 1
;     for (int t = 0; t < nt; t += 2) {
;       const bool last = (t == nt - 2);
;       const char* a1 = cA + (size_t)(t + 1) * kstep;
;       const char* a2 = last ? nA : cA + (size_t)(t + 2) * kstep; const char* b2 = last ? nB : cB + (size_t)(t + 2) * kstep;
;     ...
;     for (int a = 0; a < 2; ++a)
; #pragma unroll
;       for (int b = 0; b < 2; ++b)
; #pragma unroll
;         for (int m = 0; m < 4; ++m)
; #pragma unroll
;           for (int n = 0; n < 2; ++n) acc[a][b][m][n] = (f32x4){0.f, 0.f, 0.f, 0.f};
.LBB0_1411:
	s_add_i32 s11, s43, -2
	s_add_u32 s14, s14, 0x40080
	s_addc_u32 s15, s15, 0
	s_add_u32 s22, s18, 0x100
	v_mov_b32_e32 v2, 0
	s_addc_u32 s23, s19, 0
	s_mov_b32 s18, 0
	v_mov_b32_e32 v3, v2
	v_mov_b64_e32 v[4:5], 0
	v_mov_b64_e32 v[6:7], 0
	v_mov_b64_e32 v[8:9], 0
	v_mov_b64_e32 v[10:11], 0
	v_mov_b64_e32 v[12:13], 0
	v_mov_b64_e32 v[14:15], 0
	v_mov_b64_e32 v[16:17], 0
	v_mov_b64_e32 v[18:19], 0
	v_mov_b64_e32 v[20:21], 0
	v_mov_b64_e32 v[22:23], 0
	v_mov_b64_e32 v[24:25], 0
	v_mov_b64_e32 v[26:27], 0
	v_mov_b64_e32 v[28:29], 0
	v_mov_b64_e32 v[30:31], 0
	v_mov_b64_e32 v[32:33], 0
	v_mov_b64_e32 v[34:35], 0
	v_mov_b64_e32 v[36:37], 0
	v_mov_b64_e32 v[38:39], 0
	v_mov_b64_e32 v[40:41], 0
	v_mov_b64_e32 v[42:43], 0
	v_mov_b64_e32 v[44:45], 0
	v_mov_b64_e32 v[46:47], 0
	v_mov_b64_e32 v[48:49], 0
	v_mov_b64_e32 v[50:51], 0
	v_mov_b64_e32 v[52:53], 0
	v_mov_b64_e32 v[54:55], 0
	v_mov_b64_e32 v[56:57], 0
	v_mov_b64_e32 v[58:59], 0
	v_mov_b64_e32 v[60:61], 0
	v_mov_b64_e32 v[62:63], 0
	v_mov_b64_e32 v[64:65], 0
	v_mov_b64_e32 v[66:67], 0
	v_mov_b64_e32 v[68:69], 0
	v_mov_b64_e32 v[70:71], 0
	v_mov_b64_e32 v[72:73], 0
	v_mov_b64_e32 v[74:75], 0
	v_mov_b64_e32 v[76:77], 0
	v_mov_b64_e32 v[78:79], 0
	v_mov_b64_e32 v[80:81], 0
	v_mov_b64_e32 v[82:83], 0
	v_mov_b64_e32 v[84:85], 0
	v_mov_b64_e32 v[86:87], 0
	v_mov_b64_e32 v[88:89], 0
	v_mov_b64_e32 v[90:91], 0
	v_mov_b64_e32 v[92:93], 0
	v_mov_b64_e32 v[94:95], 0
	v_mov_b64_e32 v[96:97], 0
	v_mov_b64_e32 v[98:99], 0
	v_mov_b64_e32 v[100:101], 0
	v_mov_b64_e32 v[102:103], 0
	v_mov_b64_e32 v[104:105], 0
	v_mov_b64_e32 v[106:107], 0
	v_mov_b64_e32 v[108:109], 0
	v_mov_b64_e32 v[110:111], 0
	v_mov_b64_e32 v[112:113], 0
	v_mov_b64_e32 v[114:115], 0
	v_mov_b64_e32 v[116:117], 0
	v_mov_b64_e32 v[118:119], 0
	v_mov_b64_e32 v[120:121], 0
	v_mov_b64_e32 v[122:123], 0
	v_mov_b64_e32 v[124:125], 0
	v_mov_b64_e32 v[126:127], 0
	v_mov_b64_e32 v[128:129], 0
	.p2align	6

;   __device__ __forceinline__ const char* aptr(const Unit& u) const { return s.aptr(u); }
;   __device__ __forceinline__ const char* bptr(const Unit& u) const { return s.bptr(u); }
;   __device__ __forceinline__ bool next(int i, Unit& u) const { if (i) return false; u = u0; return true; }
; template <class Epi, class Sched>
; __device__ __forceinline__ void gemm_phase(PG8_LAS unsigned char* lds, const int lda, const int ldb, const Sched& S, const Epi& E) {
;     ...
;     const bool has_next = S.next(ui + 1, nxt);
;     const char* nA = has_next ? S.aptr(nxt) : cA; const char* nB = has_next ? S.bptr(nxt) : cB;
; #pragma unroll 1
;     for (int t = 0; t < nt; t += 2) {
;       const bool last = (t == nt - 2);
;       const char* a1 = cA + (size_t)(t + 1) * kstep;
;       const char* a2 = last ? nA : cA + (size_t)(t + 2) * kstep; const char* b2 = last ? nB : cB + (size_t)(t + 2) * kstep;
;     ...
;     for (int a = 0; a < 2; ++a)
; #pragma unroll
;       for (int b = 0; b < 2; ++b)
; #pragma unroll
;         for (int m = 0; m < 4; ++m)
; #pragma unroll
;           for (int n = 0; n < 2; ++n) acc[a][b][m][n] = (f32x4){0.f, 0.f, 0.f, 0.f};
.LBB0_1481:
	v_mov_b64_e32 v[2:3], s[8:9]
	s_ashr_i32 s11, s10, 31
	v_cmp_lt_i64_e32 vcc, s[12:13], v[2:3]
	s_lshl_b64 s[12:13], s[10:11], 19
	s_add_u32 s12, s84, s12
	s_addc_u32 s13, s85, s13
	s_and_b64 s[14:15], vcc, exec
	s_cselect_b32 s11, s13, s19
	s_cselect_b32 s50, s12, s18
	s_ashr_i32 s1, s0, 31
	s_lshl_b64 s[14:15], s[0:1], 19
	s_add_u32 s14, s30, s14
	s_addc_u32 s15, s31, s15
	s_and_b64 s[22:23], vcc, exec
	s_cselect_b32 s1, s15, s21
	s_cselect_b32 s51, s14, s20
	s_add_u32 s52, s20, 0x100
	v_mov_b32_e32 v2, 0
	s_addc_u32 s53, s21, 0
	s_mov_b32 s54, -2
	v_mov_b32_e32 v3, v2
	v_mov_b64_e32 v[4:5], 0
	v_mov_b64_e32 v[6:7], 0
	v_mov_b64_e32 v[8:9], 0
	v_mov_b64_e32 v[10:11], 0
	v_mov_b64_e32 v[12:13], 0
	v_mov_b64_e32 v[14:15], 0
	v_mov_b64_e32 v[16:17], 0
	v_mov_b64_e32 v[18:19], 0
	v_mov_b64_e32 v[20:21], 0
	v_mov_b64_e32 v[22:23], 0
	v_mov_b64_e32 v[24:25], 0
	v_mov_b64_e32 v[26:27], 0
	v_mov_b64_e32 v[28:29], 0
	v_mov_b64_e32 v[30:31], 0
	v_mov_b64_e32 v[32:33], 0
	v_mov_b64_e32 v[34:35], 0
	v_mov_b64_e32 v[36:37], 0
	v_mov_b64_e32 v[38:39], 0
	v_mov_b64_e32 v[40:41], 0
	v_mov_b64_e32 v[42:43], 0
	v_mov_b64_e32 v[44:45], 0
	v_mov_b64_e32 v[46:47], 0
	v_mov_b64_e32 v[48:49], 0
	v_mov_b64_e32 v[50:51], 0
	v_mov_b64_e32 v[52:53], 0
	v_mov_b64_e32 v[54:55], 0
	v_mov_b64_e32 v[56:57], 0
	v_mov_b64_e32 v[58:59], 0
	v_mov_b64_e32 v[60:61], 0
	v_mov_b64_e32 v[62:63], 0
	v_mov_b64_e32 v[64:65], 0
	v_mov_b64_e32 v[66:67], 0
	v_mov_b64_e32 v[68:69], 0
	v_mov_b64_e32 v[70:71], 0
	v_mov_b64_e32 v[72:73], 0
	v_mov_b64_e32 v[74:75], 0
	v_mov_b64_e32 v[76:77], 0
	v_mov_b64_e32 v[78:79], 0
	v_mov_b64_e32 v[80:81], 0
	v_mov_b64_e32 v[82:83], 0
	v_mov_b64_e32 v[84:85], 0
	v_mov_b64_e32 v[86:87], 0
	v_mov_b64_e32 v[88:89], 0
	v_mov_b64_e32 v[90:91], 0
	v_mov_b64_e32 v[92:93], 0
	v_mov_b64_e32 v[94:95], 0
	v_mov_b64_e32 v[96:97], 0
	v_mov_b64_e32 v[98:99], 0
	v_mov_b64_e32 v[100:101], 0
	v_mov_b64_e32 v[102:103], 0
	v_mov_b64_e32 v[104:105], 0
	v_mov_b64_e32 v[106:107], 0
	v_mov_b64_e32 v[108:109], 0
	v_mov_b64_e32 v[110:111], 0
	v_mov_b64_e32 v[112:113], 0
	v_mov_b64_e32 v[114:115], 0
	v_mov_b64_e32 v[116:117], 0
	v_mov_b64_e32 v[118:119], 0
	v_mov_b64_e32 v[120:121], 0
	v_mov_b64_e32 v[122:123], 0
	v_mov_b64_e32 v[124:125], 0
	v_mov_b64_e32 v[126:127], 0
	v_mov_b64_e32 v[128:129], 0
	.p2align	6

;   __device__ __forceinline__ const char* aptr(const Unit& u) const { return s.aptr(u); }
;   __device__ __forceinline__ const char* bptr(const Unit& u) const { return s.bptr(u); }
;   __device__ __forceinline__ bool next(int i, Unit& u) const { if (i) return false; u = u0; return true; }
; template <class Epi, class Sched>
; __device__ __forceinline__ void gemm_phase(PG8_LAS unsigned char* lds, const int lda, const int ldb, const Sched& S, const Epi& E) {
;     ...
;     const bool has_next = S.next(ui + 1, nxt);
;     const char* nA = has_next ? S.aptr(nxt) : cA; const char* nB = has_next ? S.bptr(nxt) : cB;
; #pragma unroll 1
;     for (int t = 0; t < nt; t += 2) {
;       const bool last = (t == nt - 2);
;       const char* a1 = cA + (size_t)(t + 1) * kstep;
;       const char* a2 = last ? nA : cA + (size_t)(t + 2) * kstep; const char* b2 = last ? nB : cB + (size_t)(t + 2) * kstep;
;     ...
;     for (int a = 0; a < 2; ++a)
; #pragma unroll
;       for (int b = 0; b < 2; ++b)
; #pragma unroll
;         for (int m = 0; m < 4; ++m)
; #pragma unroll
;           for (int n = 0; n < 2; ++n) acc[a][b][m][n] = (f32x4){0.f, 0.f, 0.f, 0.f};
.LBB0_1603:
	v_mov_b64_e32 v[2:3], s[2:3]
	s_ashr_i32 s11, s10, 31
	v_cmp_lt_i64_e32 vcc, s[12:13], v[2:3]
	s_lshl_b64 s[12:13], s[10:11], 19
	s_add_u32 s12, s58, s12
	s_addc_u32 s13, s59, s13
	s_and_b64 s[14:15], vcc, exec
	s_cselect_b32 s11, s13, s19
	s_cselect_b32 s42, s12, s18
	s_ashr_i32 s1, s0, 31
	s_lshl_b64 s[14:15], s[0:1], 19
	s_add_u32 s14, s24, s14
	s_addc_u32 s15, s25, s15
	s_and_b64 s[22:23], vcc, exec
	s_cselect_b32 s1, s15, s21
	s_cselect_b32 s43, s14, s20
	s_add_u32 s18, s18, 0x40080
	s_addc_u32 s19, s19, 0
	s_add_u32 s44, s20, 0x100
	v_mov_b32_e32 v2, 0
	s_addc_u32 s45, s21, 0
	s_mov_b32 s46, -2
	v_mov_b32_e32 v3, v2
	v_mov_b64_e32 v[4:5], 0
	v_mov_b64_e32 v[6:7], 0
	v_mov_b64_e32 v[8:9], 0
	v_mov_b64_e32 v[10:11], 0
	v_mov_b64_e32 v[12:13], 0
	v_mov_b64_e32 v[14:15], 0
	v_mov_b64_e32 v[16:17], 0
	v_mov_b64_e32 v[18:19], 0
	v_mov_b64_e32 v[20:21], 0
	v_mov_b64_e32 v[22:23], 0
	v_mov_b64_e32 v[24:25], 0
	v_mov_b64_e32 v[26:27], 0
	v_mov_b64_e32 v[28:29], 0
	v_mov_b64_e32 v[30:31], 0
	v_mov_b64_e32 v[32:33], 0
	v_mov_b64_e32 v[34:35], 0
	v_mov_b64_e32 v[36:37], 0
	v_mov_b64_e32 v[38:39], 0
	v_mov_b64_e32 v[40:41], 0
	v_mov_b64_e32 v[42:43], 0
	v_mov_b64_e32 v[44:45], 0
	v_mov_b64_e32 v[46:47], 0
	v_mov_b64_e32 v[48:49], 0
	v_mov_b64_e32 v[50:51], 0
	v_mov_b64_e32 v[52:53], 0
	v_mov_b64_e32 v[54:55], 0
	v_mov_b64_e32 v[56:57], 0
	v_mov_b64_e32 v[58:59], 0
	v_mov_b64_e32 v[60:61], 0
	v_mov_b64_e32 v[62:63], 0
	v_mov_b64_e32 v[64:65], 0
	v_mov_b64_e32 v[66:67], 0
	v_mov_b64_e32 v[68:69], 0
	v_mov_b64_e32 v[70:71], 0
	v_mov_b64_e32 v[72:73], 0
	v_mov_b64_e32 v[74:75], 0
	v_mov_b64_e32 v[76:77], 0
	v_mov_b64_e32 v[78:79], 0
	v_mov_b64_e32 v[80:81], 0
	v_mov_b64_e32 v[82:83], 0
	v_mov_b64_e32 v[84:85], 0
	v_mov_b64_e32 v[86:87], 0
	v_mov_b64_e32 v[88:89], 0
	v_mov_b64_e32 v[90:91], 0
	v_mov_b64_e32 v[92:93], 0
	v_mov_b64_e32 v[94:95], 0
	v_mov_b64_e32 v[96:97], 0
	v_mov_b64_e32 v[98:99], 0
	v_mov_b64_e32 v[100:101], 0
	v_mov_b64_e32 v[102:103], 0
	v_mov_b64_e32 v[104:105], 0
	v_mov_b64_e32 v[106:107], 0
	v_mov_b64_e32 v[108:109], 0
	v_mov_b64_e32 v[110:111], 0
	v_mov_b64_e32 v[112:113], 0
	v_mov_b64_e32 v[114:115], 0
	v_mov_b64_e32 v[116:117], 0
	v_mov_b64_e32 v[118:119], 0
	v_mov_b64_e32 v[120:121], 0
	v_mov_b64_e32 v[122:123], 0
	v_mov_b64_e32 v[124:125], 0
	v_mov_b64_e32 v[126:127], 0
	v_mov_b64_e32 v[128:129], 0
	.p2align	6

; template <class Epi, class Sched>
; __device__ __forceinline__ void gemm_phase(PG8_LAS unsigned char* lds, const int lda, const int ldb, const Sched& S, const Epi& E) {
;     ...
;     for (int a = 0; a < 2; ++a)
; #pragma unroll
;       for (int b = 0; b < 2; ++b)
; #pragma unroll
;         for (int m = 0; m < 4; ++m)
; #pragma unroll
;           for (int n = 0; n < 2; ++n) acc[a][b][m][n] = (f32x4){0.f, 0.f, 0.f, 0.f};
.LBB0_1672:
	s_add_u32 s39, s12, 0x100
	v_mov_b32_e32 v2, 0
	s_addc_u32 s40, s13, 0
	s_mov_b32 s41, -2
	v_mov_b32_e32 v3, v2
	v_mov_b64_e32 v[4:5], 0
	v_mov_b64_e32 v[6:7], 0
	v_mov_b64_e32 v[8:9], 0
	v_mov_b64_e32 v[10:11], 0
	v_mov_b64_e32 v[12:13], 0
	v_mov_b64_e32 v[14:15], 0
	v_mov_b64_e32 v[16:17], 0
	v_mov_b64_e32 v[18:19], 0
	v_mov_b64_e32 v[20:21], 0
	v_mov_b64_e32 v[22:23], 0
	v_mov_b64_e32 v[24:25], 0
	v_mov_b64_e32 v[26:27], 0
	v_mov_b64_e32 v[28:29], 0
	v_mov_b64_e32 v[30:31], 0
	v_mov_b64_e32 v[32:33], 0
	v_mov_b64_e32 v[34:35], 0
	v_mov_b64_e32 v[36:37], 0
	v_mov_b64_e32 v[38:39], 0
	v_mov_b64_e32 v[40:41], 0
	v_mov_b64_e32 v[42:43], 0
	v_mov_b64_e32 v[44:45], 0
	v_mov_b64_e32 v[46:47], 0
	v_mov_b64_e32 v[48:49], 0
	v_mov_b64_e32 v[50:51], 0
	v_mov_b64_e32 v[52:53], 0
	v_mov_b64_e32 v[54:55], 0
	v_mov_b64_e32 v[56:57], 0
	v_mov_b64_e32 v[58:59], 0
	v_mov_b64_e32 v[60:61], 0
	v_mov_b64_e32 v[62:63], 0
	v_mov_b64_e32 v[64:65], 0
	v_mov_b64_e32 v[66:67], 0
	v_mov_b64_e32 v[68:69], 0
	v_mov_b64_e32 v[70:71], 0
	v_mov_b64_e32 v[72:73], 0
	v_mov_b64_e32 v[74:75], 0
	v_mov_b64_e32 v[76:77], 0
	v_mov_b64_e32 v[78:79], 0
	v_mov_b64_e32 v[80:81], 0
	v_mov_b64_e32 v[82:83], 0
	v_mov_b64_e32 v[84:85], 0
	v_mov_b64_e32 v[86:87], 0
	v_mov_b64_e32 v[88:89], 0
	v_mov_b64_e32 v[90:91], 0
	v_mov_b64_e32 v[92:93], 0
	v_mov_b64_e32 v[94:95], 0
	v_mov_b64_e32 v[96:97], 0
	v_mov_b64_e32 v[98:99], 0
	v_mov_b64_e32 v[100:101], 0
	v_mov_b64_e32 v[102:103], 0
	v_mov_b64_e32 v[104:105], 0
	v_mov_b64_e32 v[106:107], 0
	v_mov_b64_e32 v[108:109], 0
	v_mov_b64_e32 v[110:111], 0
	v_mov_b64_e32 v[112:113], 0
	v_mov_b64_e32 v[114:115], 0
	v_mov_b64_e32 v[116:117], 0
	v_mov_b64_e32 v[118:119], 0
	v_mov_b64_e32 v[120:121], 0
	v_mov_b64_e32 v[122:123], 0
	v_mov_b64_e32 v[124:125], 0
	v_mov_b64_e32 v[126:127], 0
	v_mov_b64_e32 v[128:129], 0
	.p2align	6
